# v077: v056 + cross-half row-max exchange in the attention tile loops via v_permlane32_swap_b32 instead of ds_bpermute (prompt fast path also drops the lane-address VALU)
# speedup vs baseline: 1.0038x; 1.0018x over previous
.LBB0_1184:
	s_add_i32 s22, s67, 64
	v_cmp_le_i32_e64 s[22:23], s22, v173
	s_add_i32 s100, s67, 63
	v_cmp_gt_i32_e32 vcc, s100, v171
	s_and_b64 s[100:101], s[94:95], s[22:23]
	s_cbranch_vccnz .Lpa_A1_slow
	s_cmp_eq_u64 s[100:101], exec
	s_cbranch_scc0 .Lpa_A1_slow
	ds_read_b128 v[4:7], v175 offset:0
	ds_read_b128 v[82:85], v175 offset:6656
	ds_read_b128 v[8:11], v175 offset:32
	ds_read_b128 v[214:217], v175 offset:6688
	ds_read_b128 v[12:15], v175 offset:64
	ds_read_b128 v[218:221], v175 offset:6720
	ds_read_b128 v[188:191], v175 offset:96
	ds_read_b128 v[222:225], v175 offset:6752
	ds_read_b128 v[192:195], v175 offset:128
	ds_read_b128 v[226:229], v175 offset:6784
	ds_read_b128 v[210:213], v175 offset:160
	ds_read_b128 v[244:247], v175 offset:6816
	v_max_f32_e32 v3, v19, v19
	v_max_f32_e32 v232, v18, v18
	v_max_f32_e32 v3, v232, v3
	v_max3_f32 v3, v3, v20, v21
	v_max3_f32 v3, v3, v22, v23
	v_max3_f32 v3, v3, v24, v25
	v_max3_f32 v3, v3, v26, v27
	v_max3_f32 v3, v3, v28, v29
	v_max3_f32 v3, v3, v30, v31
	v_max3_f32 v3, v3, v32, v33
	v_max3_f32 v3, v3, v34, v35
	v_max3_f32 v3, v3, v36, v37
	v_max3_f32 v3, v3, v38, v39
	v_max3_f32 v3, v3, v40, v41
	v_max3_f32 v3, v3, v42, v43
	v_max3_f32 v3, v3, v44, v45
	v_max3_f32 v3, v3, v46, v47
	v_max3_f32 v3, v3, v48, v49
	v_mov_b32_e32 v232, v3
	s_nop 1
	v_permlane32_swap_b32 v232, v3
	v_max_f32_e32 v3, v3, v232
	v_mov_b32_e32 v233, 0x41000000
	v_sub_f32_e32 v232, v3, v186
	v_cmp_lt_f32_e64 s[100:101], v233, v232
	s_cmp_lg_u64 s[100:101], 0
	s_cbranch_scc1 .Lpa_A1_resc
	v_mov_b32_e32 v3, v186
	v_mov_b32_e32 v232, 1.0
.Lpa_A1_rjoin:
	s_waitcnt lgkmcnt(0)
	v_mfma_f32_32x32x16_bf16 v[98:113], v[4:7], v[130:133], 0
	v_sub_f32_e32 v239, v18, v3
	v_exp_f32_e32 v18, v239
	v_sub_f32_e32 v17, v19, v3
	v_exp_f32_e32 v19, v17
	v_mfma_f32_32x32x16_bf16 v[82:97], v[82:85], v[130:133], 0
	v_sub_f32_e32 v17, v20, v3
	v_exp_f32_e32 v20, v17
	v_sub_f32_e32 v17, v21, v3
	v_exp_f32_e32 v21, v17
	v_mfma_f32_32x32x16_bf16 v[98:113], v[8:11], v[134:137], v[98:113]
	v_sub_f32_e32 v17, v22, v3
	v_add_f32_e32 v239, 0, v18
	v_exp_f32_e32 v22, v17
	v_sub_f32_e32 v17, v23, v3
	v_add_f32_e32 v239, v19, v239
	v_exp_f32_e32 v23, v17
	v_mfma_f32_32x32x16_bf16 v[82:97], v[214:217], v[134:137], v[82:97]
	v_sub_f32_e32 v17, v24, v3
	v_add_f32_e32 v239, v20, v239
	v_exp_f32_e32 v24, v17
	v_sub_f32_e32 v17, v25, v3
	v_add_f32_e32 v239, v21, v239
	v_exp_f32_e32 v25, v17
	v_mfma_f32_32x32x16_bf16 v[98:113], v[12:15], v[138:141], v[98:113]
	v_sub_f32_e32 v17, v26, v3
	v_add_f32_e32 v239, v22, v239
	v_exp_f32_e32 v26, v17
	v_sub_f32_e32 v17, v27, v3
	v_add_f32_e32 v239, v23, v239
	v_exp_f32_e32 v27, v17
	v_mfma_f32_32x32x16_bf16 v[82:97], v[218:221], v[138:141], v[82:97]
	v_sub_f32_e32 v17, v28, v3
	v_add_f32_e32 v239, v24, v239
	v_exp_f32_e32 v28, v17
	v_sub_f32_e32 v17, v29, v3
	v_add_f32_e32 v239, v25, v239
	v_exp_f32_e32 v29, v17
	v_mfma_f32_32x32x16_bf16 v[98:113], v[188:191], v[142:145], v[98:113]
	v_sub_f32_e32 v17, v30, v3
	v_add_f32_e32 v239, v26, v239
	v_exp_f32_e32 v30, v17
	v_sub_f32_e32 v17, v31, v3
	v_add_f32_e32 v239, v27, v239
	v_exp_f32_e32 v31, v17
	v_mfma_f32_32x32x16_bf16 v[82:97], v[222:225], v[142:145], v[82:97]
	v_sub_f32_e32 v17, v32, v3
	v_add_f32_e32 v239, v28, v239
	v_exp_f32_e32 v32, v17
	v_sub_f32_e32 v17, v33, v3
	v_add_f32_e32 v239, v29, v239
	v_exp_f32_e32 v33, v17
	v_mfma_f32_32x32x16_bf16 v[98:113], v[192:195], v[146:149], v[98:113]
	v_sub_f32_e32 v17, v34, v3
	v_add_f32_e32 v239, v30, v239
	v_exp_f32_e32 v34, v17
	v_mfma_f32_32x32x16_bf16 v[82:97], v[226:229], v[146:149], v[82:97]
	v_sub_f32_e32 v17, v35, v3
	v_add_f32_e32 v239, v31, v239
	v_exp_f32_e32 v35, v17
	v_mfma_f32_32x32x16_bf16 v[98:113], v[210:213], v[150:153], v[98:113]
	v_sub_f32_e32 v17, v36, v3
	v_add_f32_e32 v239, v32, v239
	v_exp_f32_e32 v36, v17
	v_mfma_f32_32x32x16_bf16 v[82:97], v[244:247], v[150:153], v[82:97]
	v_sub_f32_e32 v17, v37, v3
	v_add_f32_e32 v239, v33, v239
	v_exp_f32_e32 v37, v17
	ds_read_b64_tr_b16 v[4:5], v177 offset:0
	ds_read_b64_tr_b16 v[6:7], v177 offset:1536
	ds_read_b64_tr_b16 v[8:9], v177 offset:64
	ds_read_b64_tr_b16 v[10:11], v177 offset:1600
	ds_read_b64_tr_b16 v[12:13], v177 offset:3072
	ds_read_b64_tr_b16 v[14:15], v177 offset:4608
	ds_read_b64_tr_b16 v[188:189], v177 offset:3136
	ds_read_b64_tr_b16 v[190:191], v177 offset:4672
	ds_read_b64_tr_b16 v[192:193], v177 offset:6144
	ds_read_b64_tr_b16 v[194:195], v177 offset:7680
	ds_read_b64_tr_b16 v[210:211], v177 offset:6208
	ds_read_b64_tr_b16 v[212:213], v177 offset:7744
	ds_read_b64_tr_b16 v[214:215], v177 offset:9216
	ds_read_b64_tr_b16 v[216:217], v177 offset:10752
	ds_read_b64_tr_b16 v[218:219], v177 offset:9280
	ds_read_b64_tr_b16 v[220:221], v177 offset:10816
	v_sub_f32_e32 v17, v38, v3
	v_add_f32_e32 v239, v34, v239
	v_exp_f32_e32 v38, v17
	v_sub_f32_e32 v17, v39, v3
	v_add_f32_e32 v239, v35, v239
	v_exp_f32_e32 v39, v17
	v_sub_f32_e32 v17, v40, v3
	v_add_f32_e32 v239, v36, v239
	v_exp_f32_e32 v40, v17
	v_sub_f32_e32 v17, v41, v3
	v_add_f32_e32 v239, v37, v239
	v_exp_f32_e32 v41, v17
	v_cvt_pk_bf16_f32 v222, v18, v19
	v_cvt_pk_bf16_f32 v223, v20, v21
	v_cvt_pk_bf16_f32 v224, v22, v23
	v_cvt_pk_bf16_f32 v225, v24, v25
	v_cvt_pk_bf16_f32 v226, v26, v27
	v_cvt_pk_bf16_f32 v227, v28, v29
	v_cvt_pk_bf16_f32 v228, v30, v31
	v_cvt_pk_bf16_f32 v229, v32, v33
	v_cvt_pk_bf16_f32 v244, v34, v35
	v_cvt_pk_bf16_f32 v245, v36, v37
	v_cvt_pk_bf16_f32 v246, v38, v39
	v_cvt_pk_bf16_f32 v247, v40, v41
	s_waitcnt lgkmcnt(0)
	v_mfma_f32_32x32x16_bf16 v[66:81], v[4:7], v[222:225], v[66:81]
	v_sub_f32_e32 v17, v42, v3
	v_add_f32_e32 v239, v38, v239
	v_exp_f32_e32 v42, v17
	v_sub_f32_e32 v17, v43, v3
	v_add_f32_e32 v239, v39, v239
	v_exp_f32_e32 v43, v17
	v_mfma_f32_32x32x16_bf16 v[50:65], v[8:11], v[222:225], v[50:65]
	v_sub_f32_e32 v17, v44, v3
	v_add_f32_e32 v239, v40, v239
	v_exp_f32_e32 v44, v17
	v_sub_f32_e32 v17, v45, v3
	v_add_f32_e32 v239, v41, v239
	v_exp_f32_e32 v45, v17
	v_mfma_f32_32x32x16_bf16 v[66:81], v[12:15], v[226:229], v[66:81]
	v_sub_f32_e32 v17, v46, v3
	v_add_f32_e32 v239, v42, v239
	v_exp_f32_e32 v46, v17
	v_sub_f32_e32 v17, v47, v3
	v_add_f32_e32 v239, v43, v239
	v_exp_f32_e32 v47, v17
	v_mfma_f32_32x32x16_bf16 v[50:65], v[188:191], v[226:229], v[50:65]
	v_sub_f32_e32 v17, v48, v3
	v_add_f32_e32 v239, v44, v239
	v_exp_f32_e32 v48, v17
	v_sub_f32_e32 v17, v49, v3
	v_add_f32_e32 v239, v45, v239
	v_exp_f32_e32 v49, v17
	v_mfma_f32_32x32x16_bf16 v[66:81], v[192:195], v[244:247], v[66:81]
	v_add_f32_e32 v239, v46, v239
	v_add_f32_e32 v239, v47, v239
	v_add_f32_e32 v239, v48, v239
	v_add_f32_e32 v16, v49, v239
	v_fmac_f32_e32 v16, v185, v232
	v_mov_b32_e32 v185, v16
	v_mov_b32_e32 v186, v3
	v_mfma_f32_32x32x16_bf16 v[50:65], v[210:213], v[244:247], v[50:65]
	v_cvt_pk_bf16_f32 v248, v42, v43
	v_cvt_pk_bf16_f32 v249, v44, v45
	v_cvt_pk_bf16_f32 v250, v46, v47
	v_cvt_pk_bf16_f32 v251, v48, v49
	s_nop 1
	v_mfma_f32_32x32x16_bf16 v[66:81], v[214:217], v[248:251], v[66:81]
	v_mfma_f32_32x32x16_bf16 v[50:65], v[218:221], v[248:251], v[50:65]
	s_branch .LBB0_1194

.LBB0_1219:
	s_add_i32 s100, s67, 128
	v_cmp_le_i32_e32 vcc, s100, v173
	s_add_i32 s101, s67, 127
	s_and_b64 vcc, s[94:95], vcc
	s_cmp_eq_u64 vcc, exec
	s_cbranch_scc0 .Lpa_A2_slow
	v_cmp_gt_i32_e32 vcc, s101, v171
	s_cbranch_vccnz .Lpa_A2_slow
	ds_read_b128 v[4:7], v174 offset:0
	ds_read_b128 v[34:37], v174 offset:6656
	ds_read_b128 v[8:11], v174 offset:32
	ds_read_b128 v[214:217], v174 offset:6688
	ds_read_b128 v[12:15], v174 offset:64
	ds_read_b128 v[218:221], v174 offset:6720
	ds_read_b128 v[188:191], v174 offset:96
	ds_read_b128 v[222:225], v174 offset:6752
	ds_read_b128 v[192:195], v174 offset:128
	ds_read_b128 v[226:229], v174 offset:6784
	ds_read_b128 v[210:213], v174 offset:160
	ds_read_b128 v[244:247], v174 offset:6816
	v_max_f32_e32 v3, v99, v99
	v_max_f32_e32 v232, v98, v98
	v_max_f32_e32 v3, v232, v3
	v_max3_f32 v3, v3, v100, v101
	v_max3_f32 v3, v3, v102, v103
	v_max3_f32 v3, v3, v104, v105
	v_max3_f32 v3, v3, v106, v107
	v_max3_f32 v3, v3, v108, v109
	v_max3_f32 v3, v3, v110, v111
	v_max3_f32 v3, v3, v112, v113
	v_max3_f32 v3, v3, v82, v83
	v_max3_f32 v3, v3, v84, v85
	v_max3_f32 v3, v3, v86, v87
	v_max3_f32 v3, v3, v88, v89
	v_max3_f32 v3, v3, v90, v91
	v_max3_f32 v3, v3, v92, v93
	v_max3_f32 v3, v3, v94, v95
	v_max3_f32 v3, v3, v96, v97
	v_mov_b32_e32 v232, v3
	s_nop 1
	v_permlane32_swap_b32 v232, v3
	v_max_f32_e32 v3, v3, v232
	v_mov_b32_e32 v233, 0x41000000
	v_sub_f32_e32 v232, v3, v186
	v_cmp_lt_f32_e64 s[100:101], v233, v232
	s_cmp_lg_u64 s[100:101], 0
	s_cbranch_scc1 .Lpa_A2_resc
	v_mov_b32_e32 v3, v186
	v_mov_b32_e32 v232, 1.0
.Lpa_A2_rjoin:
	s_waitcnt lgkmcnt(0)
	v_mfma_f32_32x32x16_bf16 v[18:33], v[4:7], v[130:133], 0
	v_sub_f32_e32 v239, v98, v3
	v_exp_f32_e32 v98, v239
	v_sub_f32_e32 v17, v99, v3
	v_exp_f32_e32 v99, v17
	v_mfma_f32_32x32x16_bf16 v[34:49], v[34:37], v[130:133], 0
	v_sub_f32_e32 v17, v100, v3
	v_exp_f32_e32 v100, v17
	v_sub_f32_e32 v17, v101, v3
	v_exp_f32_e32 v101, v17
	v_mfma_f32_32x32x16_bf16 v[18:33], v[8:11], v[134:137], v[18:33]
	v_sub_f32_e32 v17, v102, v3
	v_add_f32_e32 v239, 0, v98
	v_exp_f32_e32 v102, v17
	v_sub_f32_e32 v17, v103, v3
	v_add_f32_e32 v239, v99, v239
	v_exp_f32_e32 v103, v17
	v_mfma_f32_32x32x16_bf16 v[34:49], v[214:217], v[134:137], v[34:49]
	v_sub_f32_e32 v17, v104, v3
	v_add_f32_e32 v239, v100, v239
	v_exp_f32_e32 v104, v17
	v_sub_f32_e32 v17, v105, v3
	v_add_f32_e32 v239, v101, v239
	v_exp_f32_e32 v105, v17
	v_mfma_f32_32x32x16_bf16 v[18:33], v[12:15], v[138:141], v[18:33]
	v_sub_f32_e32 v17, v106, v3
	v_add_f32_e32 v239, v102, v239
	v_exp_f32_e32 v106, v17
	v_sub_f32_e32 v17, v107, v3
	v_add_f32_e32 v239, v103, v239
	v_exp_f32_e32 v107, v17
	v_mfma_f32_32x32x16_bf16 v[34:49], v[218:221], v[138:141], v[34:49]
	v_sub_f32_e32 v17, v108, v3
	v_add_f32_e32 v239, v104, v239
	v_exp_f32_e32 v108, v17
	v_sub_f32_e32 v17, v109, v3
	v_add_f32_e32 v239, v105, v239
	v_exp_f32_e32 v109, v17
	v_mfma_f32_32x32x16_bf16 v[18:33], v[188:191], v[142:145], v[18:33]
	v_sub_f32_e32 v17, v110, v3
	v_add_f32_e32 v239, v106, v239
	v_exp_f32_e32 v110, v17
	v_sub_f32_e32 v17, v111, v3
	v_add_f32_e32 v239, v107, v239
	v_exp_f32_e32 v111, v17
	v_mfma_f32_32x32x16_bf16 v[34:49], v[222:225], v[142:145], v[34:49]
	v_sub_f32_e32 v17, v112, v3
	v_add_f32_e32 v239, v108, v239
	v_exp_f32_e32 v112, v17
	v_sub_f32_e32 v17, v113, v3
	v_add_f32_e32 v239, v109, v239
	v_exp_f32_e32 v113, v17
	v_mfma_f32_32x32x16_bf16 v[18:33], v[192:195], v[146:149], v[18:33]
	v_sub_f32_e32 v17, v82, v3
	v_add_f32_e32 v239, v110, v239
	v_exp_f32_e32 v82, v17
	v_mfma_f32_32x32x16_bf16 v[34:49], v[226:229], v[146:149], v[34:49]
	v_sub_f32_e32 v17, v83, v3
	v_add_f32_e32 v239, v111, v239
	v_exp_f32_e32 v83, v17
	v_mfma_f32_32x32x16_bf16 v[18:33], v[210:213], v[150:153], v[18:33]
	v_sub_f32_e32 v17, v84, v3
	v_add_f32_e32 v239, v112, v239
	v_exp_f32_e32 v84, v17
	v_mfma_f32_32x32x16_bf16 v[34:49], v[244:247], v[150:153], v[34:49]
	v_sub_f32_e32 v17, v85, v3
	v_add_f32_e32 v239, v113, v239
	v_exp_f32_e32 v85, v17
	ds_read_b64_tr_b16 v[4:5], v178 offset:0
	ds_read_b64_tr_b16 v[6:7], v178 offset:1536
	ds_read_b64_tr_b16 v[8:9], v178 offset:64
	ds_read_b64_tr_b16 v[10:11], v178 offset:1600
	ds_read_b64_tr_b16 v[12:13], v178 offset:3072
	ds_read_b64_tr_b16 v[14:15], v178 offset:4608
	ds_read_b64_tr_b16 v[188:189], v178 offset:3136
	ds_read_b64_tr_b16 v[190:191], v178 offset:4672
	ds_read_b64_tr_b16 v[192:193], v178 offset:6144
	ds_read_b64_tr_b16 v[194:195], v178 offset:7680
	ds_read_b64_tr_b16 v[210:211], v178 offset:6208
	ds_read_b64_tr_b16 v[212:213], v178 offset:7744
	ds_read_b64_tr_b16 v[214:215], v178 offset:9216
	ds_read_b64_tr_b16 v[216:217], v178 offset:10752
	ds_read_b64_tr_b16 v[218:219], v178 offset:9280
	ds_read_b64_tr_b16 v[220:221], v178 offset:10816
	v_sub_f32_e32 v17, v86, v3
	v_add_f32_e32 v239, v82, v239
	v_exp_f32_e32 v86, v17
	v_sub_f32_e32 v17, v87, v3
	v_add_f32_e32 v239, v83, v239
	v_exp_f32_e32 v87, v17
	v_sub_f32_e32 v17, v88, v3
	v_add_f32_e32 v239, v84, v239
	v_exp_f32_e32 v88, v17
	v_sub_f32_e32 v17, v89, v3
	v_add_f32_e32 v239, v85, v239
	v_exp_f32_e32 v89, v17
	v_cvt_pk_bf16_f32 v222, v98, v99
	v_cvt_pk_bf16_f32 v223, v100, v101
	v_cvt_pk_bf16_f32 v224, v102, v103
	v_cvt_pk_bf16_f32 v225, v104, v105
	v_cvt_pk_bf16_f32 v226, v106, v107
	v_cvt_pk_bf16_f32 v227, v108, v109
	v_cvt_pk_bf16_f32 v228, v110, v111
	v_cvt_pk_bf16_f32 v229, v112, v113
	v_cvt_pk_bf16_f32 v244, v82, v83
	v_cvt_pk_bf16_f32 v245, v84, v85
	v_cvt_pk_bf16_f32 v246, v86, v87
	v_cvt_pk_bf16_f32 v247, v88, v89
	s_waitcnt lgkmcnt(0)
	v_mfma_f32_32x32x16_bf16 v[66:81], v[4:7], v[222:225], v[66:81]
	v_sub_f32_e32 v17, v90, v3
	v_add_f32_e32 v239, v86, v239
	v_exp_f32_e32 v90, v17
	v_sub_f32_e32 v17, v91, v3
	v_add_f32_e32 v239, v87, v239
	v_exp_f32_e32 v91, v17
	v_mfma_f32_32x32x16_bf16 v[50:65], v[8:11], v[222:225], v[50:65]
	v_sub_f32_e32 v17, v92, v3
	v_add_f32_e32 v239, v88, v239
	v_exp_f32_e32 v92, v17
	v_sub_f32_e32 v17, v93, v3
	v_add_f32_e32 v239, v89, v239
	v_exp_f32_e32 v93, v17
	v_mfma_f32_32x32x16_bf16 v[66:81], v[12:15], v[226:229], v[66:81]
	v_sub_f32_e32 v17, v94, v3
	v_add_f32_e32 v239, v90, v239
	v_exp_f32_e32 v94, v17
	v_sub_f32_e32 v17, v95, v3
	v_add_f32_e32 v239, v91, v239
	v_exp_f32_e32 v95, v17
	v_mfma_f32_32x32x16_bf16 v[50:65], v[188:191], v[226:229], v[50:65]
	v_sub_f32_e32 v17, v96, v3
	v_add_f32_e32 v239, v92, v239
	v_exp_f32_e32 v96, v17
	v_sub_f32_e32 v17, v97, v3
	v_add_f32_e32 v239, v93, v239
	v_exp_f32_e32 v97, v17
	v_mfma_f32_32x32x16_bf16 v[66:81], v[192:195], v[244:247], v[66:81]
	v_add_f32_e32 v239, v94, v239
	v_add_f32_e32 v239, v95, v239
	v_add_f32_e32 v239, v96, v239
	v_add_f32_e32 v16, v97, v239
	v_fmac_f32_e32 v16, v185, v232
	v_mov_b32_e32 v185, v16
	v_mov_b32_e32 v186, v3
	v_mfma_f32_32x32x16_bf16 v[50:65], v[210:213], v[244:247], v[50:65]
	v_cvt_pk_bf16_f32 v248, v90, v91
	v_cvt_pk_bf16_f32 v249, v92, v93
	v_cvt_pk_bf16_f32 v250, v94, v95
	v_cvt_pk_bf16_f32 v251, v96, v97
	s_nop 1
	v_mfma_f32_32x32x16_bf16 v[66:81], v[214:217], v[248:251], v[66:81]
	v_mfma_f32_32x32x16_bf16 v[50:65], v[218:221], v[248:251], v[50:65]
	s_branch .LBB0_1217

.LmaskA_join:
	v_max_f32_e32 v3, v147, v8
	v_max3_f32 v3, v3, v9, v10
	v_max3_f32 v3, v3, v11, v12
	v_max3_f32 v3, v3, v13, v14
	v_max3_f32 v3, v3, v4, v5
	v_max3_f32 v3, v3, v6, v7
	v_max3_f32 v3, v3, v15, v16
	v_max3_f32 v3, v3, v17, v146
	v_mov_b32_e32 v148, v3
	s_nop 1
	v_permlane32_swap_b32 v148, v3
	v_max_f32_e32 v148, v3, v148
	v_mov_b32_e32 v233, 0x41000000
	v_sub_f32_e32 v3, v148, v166
	v_cmp_lt_f32_e64 s[100:101], v233, v3
	s_cmp_lg_u64 s[100:101], 0
	s_cbranch_scc1 .LlazyA_rescale
	v_mov_b32_e32 v3, v166
	v_mov_b32_e32 v148, 0

.LBB0_1637:
	s_add_i32 s22, s67, 64
	v_cmp_le_i32_e64 s[22:23], s22, v173
	s_add_i32 s100, s67, 63
	v_cmp_gt_i32_e32 vcc, s100, v171
	s_and_b64 s[100:101], s[74:75], s[22:23]
	s_cbranch_vccnz .Lpa_B1_slow
	s_cmp_eq_u64 s[100:101], exec
	s_cbranch_scc0 .Lpa_B1_slow
	ds_read_b128 v[4:7], v175 offset:0
	ds_read_b128 v[82:85], v175 offset:6656
	ds_read_b128 v[8:11], v175 offset:32
	ds_read_b128 v[214:217], v175 offset:6688
	ds_read_b128 v[12:15], v175 offset:64
	ds_read_b128 v[218:221], v175 offset:6720
	ds_read_b128 v[188:191], v175 offset:96
	ds_read_b128 v[222:225], v175 offset:6752
	ds_read_b128 v[192:195], v175 offset:128
	ds_read_b128 v[226:229], v175 offset:6784
	ds_read_b128 v[210:213], v175 offset:160
	ds_read_b128 v[244:247], v175 offset:6816
	v_max_f32_e32 v3, v19, v19
	v_max_f32_e32 v232, v18, v18
	v_max_f32_e32 v3, v232, v3
	v_max3_f32 v3, v3, v20, v21
	v_max3_f32 v3, v3, v22, v23
	v_max3_f32 v3, v3, v24, v25
	v_max3_f32 v3, v3, v26, v27
	v_max3_f32 v3, v3, v28, v29
	v_max3_f32 v3, v3, v30, v31
	v_max3_f32 v3, v3, v32, v33
	v_max3_f32 v3, v3, v34, v35
	v_max3_f32 v3, v3, v36, v37
	v_max3_f32 v3, v3, v38, v39
	v_max3_f32 v3, v3, v40, v41
	v_max3_f32 v3, v3, v42, v43
	v_max3_f32 v3, v3, v44, v45
	v_max3_f32 v3, v3, v46, v47
	v_max3_f32 v3, v3, v48, v49
	v_mov_b32_e32 v232, v3
	s_nop 1
	v_permlane32_swap_b32 v232, v3
	v_max_f32_e32 v3, v3, v232
	v_mov_b32_e32 v233, 0x41000000
	v_sub_f32_e32 v232, v3, v186
	v_cmp_lt_f32_e64 s[100:101], v233, v232
	s_cmp_lg_u64 s[100:101], 0
	s_cbranch_scc1 .Lpa_B1_resc
	v_mov_b32_e32 v3, v186
	v_mov_b32_e32 v232, 1.0

.LBB0_1672:
	s_add_i32 s100, s67, 128
	v_cmp_le_i32_e32 vcc, s100, v173
	s_add_i32 s101, s67, 127
	s_and_b64 vcc, s[74:75], vcc
	s_cmp_eq_u64 vcc, exec
	s_cbranch_scc0 .Lpa_B2_slow
	v_cmp_gt_i32_e32 vcc, s101, v171
	s_cbranch_vccnz .Lpa_B2_slow
	ds_read_b128 v[4:7], v174 offset:0
	ds_read_b128 v[34:37], v174 offset:6656
	ds_read_b128 v[8:11], v174 offset:32
	ds_read_b128 v[214:217], v174 offset:6688
	ds_read_b128 v[12:15], v174 offset:64
	ds_read_b128 v[218:221], v174 offset:6720
	ds_read_b128 v[188:191], v174 offset:96
	ds_read_b128 v[222:225], v174 offset:6752
	ds_read_b128 v[192:195], v174 offset:128
	ds_read_b128 v[226:229], v174 offset:6784
	ds_read_b128 v[210:213], v174 offset:160
	ds_read_b128 v[244:247], v174 offset:6816
	v_max_f32_e32 v3, v99, v99
	v_max_f32_e32 v232, v98, v98
	v_max_f32_e32 v3, v232, v3
	v_max3_f32 v3, v3, v100, v101
	v_max3_f32 v3, v3, v102, v103
	v_max3_f32 v3, v3, v104, v105
	v_max3_f32 v3, v3, v106, v107
	v_max3_f32 v3, v3, v108, v109
	v_max3_f32 v3, v3, v110, v111
	v_max3_f32 v3, v3, v112, v113
	v_max3_f32 v3, v3, v82, v83
	v_max3_f32 v3, v3, v84, v85
	v_max3_f32 v3, v3, v86, v87
	v_max3_f32 v3, v3, v88, v89
	v_max3_f32 v3, v3, v90, v91
	v_max3_f32 v3, v3, v92, v93
	v_max3_f32 v3, v3, v94, v95
	v_max3_f32 v3, v3, v96, v97
	v_mov_b32_e32 v232, v3
	s_nop 1
	v_permlane32_swap_b32 v232, v3
	v_max_f32_e32 v3, v3, v232
	v_mov_b32_e32 v233, 0x41000000
	v_sub_f32_e32 v232, v3, v186
	v_cmp_lt_f32_e64 s[100:101], v233, v232
	s_cmp_lg_u64 s[100:101], 0
	s_cbranch_scc1 .Lpa_B2_resc
	v_mov_b32_e32 v3, v186
	v_mov_b32_e32 v232, 1.0
